# fused lean-tile block in P4 (both 32-key sub-tiles of a far tile software-pipelined, QK of the next sub-tile under the softmax of the previous)
# speedup vs baseline: 1.0210x; 1.0210x over previous
.LBB0_658:
	s_and_b64 vcc, exec, s[0:1]
	s_cbranch_vccz .LBB0_653
	s_lshl_b32 s0, s76, 14
	s_or_b32 s76, s0, s21
	s_lshl_b32 s77, s77, 6
	s_add_i32 s78, s77, 63
	s_cmp_gt_i32 s78, s72
	s_cbranch_scc1 .Lflt_no
	s_cmp_lt_i32 s77, s71
	s_cbranch_scc1 .Lflt_no
	s_sub_i32 s0, s33, s78
	s_cmpk_gt_i32 s0, 0x7f
	s_cselect_b64 s[0:1], -1, 0
	s_or_b64 s[0:1], s[0:1], s[30:31]
	s_and_b64 vcc, exec, s[0:1]
	s_cbranch_vccz .Lflt_no
	v_add_u32_e32 v3, s76, v198
	ds_read_b128 v[4:7], v3
	v_add_u32_e32 v16, s76, v206
	ds_read_b128 v[8:11], v16
	v_add_u32_e32 v17, s76, v207
	ds_read_b128 v[12:15], v17
	v_add_u32_e32 v238, s76, v208
	ds_read_b128 v[214:217], v238
	ds_read_b128 v[234:237], v3 offset:4096
	ds_read_b128 v[244:247], v16 offset:4096
	ds_read_b128 v[248:251], v17 offset:4096
	ds_read_b128 v[252:255], v238 offset:4096
	s_setprio 1
	s_waitcnt lgkmcnt(7)
	v_mfma_f32_32x32x16_bf16 v[118:133], v[4:7], v[134:137], v[86:101]
	s_waitcnt lgkmcnt(6)
	v_mfma_f32_32x32x16_bf16 v[118:133], v[8:11], v[138:141], v[118:133]
	s_waitcnt lgkmcnt(5)
	v_mfma_f32_32x32x16_bf16 v[118:133], v[12:15], v[142:145], v[118:133]
	s_waitcnt lgkmcnt(4)
	v_mfma_f32_32x32x16_bf16 v[118:133], v[214:217], v[150:153], v[118:133]
	s_add_i32 s0, s76, 0x2000
	v_mfma_f32_32x32x16_bf16 v[102:117], v[4:7], v[146:149], v[86:101]
	v_add_u32_e32 v3, s0, v200
	ds_read_b64_tr_b16 v[4:5], v3 offset:0
	ds_read_b64_tr_b16 v[6:7], v3 offset:1024
	v_mfma_f32_32x32x16_bf16 v[102:117], v[8:11], v[154:157], v[102:117]
	ds_read_b64_tr_b16 v[8:9], v3 offset:2048
	ds_read_b64_tr_b16 v[10:11], v3 offset:3072
	s_nop 4
	v_exp_f32_e32 v118, v118
	v_exp_f32_e32 v119, v119
	v_exp_f32_e32 v120, v120
	v_mfma_f32_32x32x16_bf16 v[102:117], v[12:15], v[158:161], v[102:117]
	v_add_u32_e32 v3, s0, v201
	ds_read_b64_tr_b16 v[12:13], v3 offset:0
	ds_read_b64_tr_b16 v[14:15], v3 offset:1024
	v_exp_f32_e32 v121, v121
	v_exp_f32_e32 v122, v122
	v_exp_f32_e32 v123, v123
	v_mfma_f32_32x32x16_bf16 v[102:117], v[214:217], v[162:165], v[102:117]
	ds_read_b64_tr_b16 v[214:215], v3 offset:2048
	ds_read_b64_tr_b16 v[216:217], v3 offset:3072
	v_exp_f32_e32 v124, v124
	v_exp_f32_e32 v125, v125
	v_exp_f32_e32 v126, v126
	s_waitcnt lgkmcnt(8)
	v_mfma_f32_32x32x16_bf16 v[218:233], v[234:237], v[134:137], v[86:101]
	v_exp_f32_e32 v127, v127
	v_exp_f32_e32 v128, v128
	v_exp_f32_e32 v129, v129
	v_mfma_f32_32x32x16_bf16 v[218:233], v[244:247], v[138:141], v[218:233]
	v_exp_f32_e32 v130, v130
	v_exp_f32_e32 v131, v131
	v_exp_f32_e32 v132, v132
	v_mfma_f32_32x32x16_bf16 v[218:233], v[248:251], v[142:145], v[218:233]
	v_exp_f32_e32 v133, v133
	v_pk_add_f32 v[16:17], v[118:119], v[120:121]
	v_pk_add_f32 v[16:17], v[16:17], v[122:123]
	v_pk_add_f32 v[16:17], v[16:17], v[124:125]
	v_cvt_pk_bf16_f32 v118, v118, v119
	v_cvt_pk_bf16_f32 v119, v120, v121
	v_cvt_pk_bf16_f32 v120, v122, v123
	v_mfma_f32_32x32x16_bf16 v[218:233], v[252:255], v[150:153], v[218:233]
	v_cvt_pk_bf16_f32 v121, v124, v125
	v_cvt_pk_bf16_f32 v122, v126, v127
	v_cvt_pk_bf16_f32 v123, v128, v129
	v_cvt_pk_bf16_f32 v124, v130, v131
	v_cvt_pk_bf16_f32 v125, v132, v133
	v_pk_add_f32 v[16:17], v[16:17], v[126:127]
	v_pk_add_f32 v[16:17], v[16:17], v[128:129]
	v_pk_add_f32 v[16:17], v[16:17], v[130:131]
	v_pk_add_f32 v[16:17], v[16:17], v[132:133]
	s_waitcnt lgkmcnt(0)
	v_mfma_f32_32x32x16_bf16 v[20:35], v[4:7], v[118:121], v[20:35]
	v_exp_f32_e32 v102, v102
	v_exp_f32_e32 v103, v103
	v_exp_f32_e32 v104, v104
	v_mfma_f32_32x32x16_bf16 v[36:51], v[12:15], v[118:121], v[36:51]
	v_exp_f32_e32 v105, v105
	v_exp_f32_e32 v106, v106
	v_exp_f32_e32 v107, v107
	v_mfma_f32_32x32x16_bf16 v[20:35], v[8:11], v[122:125], v[20:35]
	v_exp_f32_e32 v108, v108
	v_exp_f32_e32 v109, v109
	v_exp_f32_e32 v110, v110
	v_mfma_f32_32x32x16_bf16 v[36:51], v[214:217], v[122:125], v[36:51]
	v_exp_f32_e32 v111, v111
	v_exp_f32_e32 v112, v112
	v_exp_f32_e32 v113, v113
	s_add_i32 s0, s76, 0x3000
	v_mfma_f32_32x32x16_bf16 v[118:133], v[234:237], v[146:149], v[86:101]
	v_add_u32_e32 v3, s0, v200
	ds_read_b64_tr_b16 v[234:235], v3 offset:0
	ds_read_b64_tr_b16 v[236:237], v3 offset:1024
	v_exp_f32_e32 v114, v114
	v_exp_f32_e32 v115, v115
	v_exp_f32_e32 v116, v116
	v_mfma_f32_32x32x16_bf16 v[118:133], v[244:247], v[154:157], v[118:133]
	ds_read_b64_tr_b16 v[244:245], v3 offset:2048
	ds_read_b64_tr_b16 v[246:247], v3 offset:3072
	v_exp_f32_e32 v117, v117
	v_pk_add_f32 v[238:239], v[102:103], v[104:105]
	v_pk_add_f32 v[238:239], v[238:239], v[106:107]
	v_pk_add_f32 v[238:239], v[238:239], v[108:109]
	v_cvt_pk_bf16_f32 v102, v102, v103
	v_cvt_pk_bf16_f32 v103, v104, v105
	v_mfma_f32_32x32x16_bf16 v[118:133], v[248:251], v[158:161], v[118:133]
	v_add_u32_e32 v3, s0, v201
	ds_read_b64_tr_b16 v[248:249], v3 offset:0
	ds_read_b64_tr_b16 v[250:251], v3 offset:1024
	v_cvt_pk_bf16_f32 v104, v106, v107
	v_cvt_pk_bf16_f32 v105, v108, v109
	v_cvt_pk_bf16_f32 v106, v110, v111
	v_cvt_pk_bf16_f32 v107, v112, v113
	v_cvt_pk_bf16_f32 v108, v114, v115
	v_cvt_pk_bf16_f32 v109, v116, v117
	v_mfma_f32_32x32x16_bf16 v[118:133], v[252:255], v[162:165], v[118:133]
	ds_read_b64_tr_b16 v[252:253], v3 offset:2048
	ds_read_b64_tr_b16 v[254:255], v3 offset:3072
	v_pk_add_f32 v[238:239], v[238:239], v[110:111]
	v_pk_add_f32 v[238:239], v[238:239], v[112:113]
	v_pk_add_f32 v[238:239], v[238:239], v[114:115]
	v_pk_add_f32 v[238:239], v[238:239], v[116:117]
	v_mfma_f32_32x32x16_bf16 v[68:83], v[4:7], v[102:105], v[68:83]
	v_exp_f32_e32 v218, v218
	v_exp_f32_e32 v219, v219
	v_exp_f32_e32 v220, v220
	v_mfma_f32_32x32x16_bf16 v[52:67], v[12:15], v[102:105], v[52:67]
	v_exp_f32_e32 v221, v221
	v_exp_f32_e32 v222, v222
	v_exp_f32_e32 v223, v223
	v_mfma_f32_32x32x16_bf16 v[68:83], v[8:11], v[106:109], v[68:83]
	v_exp_f32_e32 v224, v224
	v_exp_f32_e32 v225, v225
	v_exp_f32_e32 v226, v226
	v_mfma_f32_32x32x16_bf16 v[52:67], v[214:217], v[106:109], v[52:67]
	v_exp_f32_e32 v227, v227
	v_exp_f32_e32 v228, v228
	v_exp_f32_e32 v229, v229
	v_exp_f32_e32 v230, v230
	v_exp_f32_e32 v231, v231
	v_exp_f32_e32 v232, v232
	v_exp_f32_e32 v233, v233
	v_pk_add_f32 v[16:17], v[16:17], v[218:219]
	v_pk_add_f32 v[16:17], v[16:17], v[220:221]
	v_pk_add_f32 v[16:17], v[16:17], v[222:223]
	v_pk_add_f32 v[16:17], v[16:17], v[224:225]
	v_cvt_pk_bf16_f32 v218, v218, v219
	v_cvt_pk_bf16_f32 v219, v220, v221
	v_cvt_pk_bf16_f32 v220, v222, v223
	v_cvt_pk_bf16_f32 v221, v224, v225
	v_cvt_pk_bf16_f32 v222, v226, v227
	v_cvt_pk_bf16_f32 v223, v228, v229
	v_cvt_pk_bf16_f32 v224, v230, v231
	v_cvt_pk_bf16_f32 v225, v232, v233
	s_waitcnt lgkmcnt(0)
	v_mfma_f32_32x32x16_bf16 v[20:35], v[234:237], v[218:221], v[20:35]
	v_exp_f32_e32 v118, v118
	v_exp_f32_e32 v119, v119
	v_exp_f32_e32 v120, v120
	v_mfma_f32_32x32x16_bf16 v[36:51], v[248:251], v[218:221], v[36:51]
	v_exp_f32_e32 v121, v121
	v_exp_f32_e32 v122, v122
	v_exp_f32_e32 v123, v123
	v_mfma_f32_32x32x16_bf16 v[20:35], v[244:247], v[222:225], v[20:35]
	v_exp_f32_e32 v124, v124
	v_exp_f32_e32 v125, v125
	v_exp_f32_e32 v126, v126
	v_mfma_f32_32x32x16_bf16 v[36:51], v[252:255], v[222:225], v[36:51]
	v_exp_f32_e32 v127, v127
	v_exp_f32_e32 v128, v128
	v_exp_f32_e32 v129, v129
	v_exp_f32_e32 v130, v130
	v_exp_f32_e32 v131, v131
	v_exp_f32_e32 v132, v132
	v_exp_f32_e32 v133, v133
	v_pk_add_f32 v[238:239], v[238:239], v[118:119]
	v_pk_add_f32 v[238:239], v[238:239], v[120:121]
	v_pk_add_f32 v[238:239], v[238:239], v[122:123]
	v_pk_add_f32 v[238:239], v[238:239], v[124:125]
	v_cvt_pk_bf16_f32 v118, v118, v119
	v_cvt_pk_bf16_f32 v119, v120, v121
	v_cvt_pk_bf16_f32 v120, v122, v123
	v_cvt_pk_bf16_f32 v121, v124, v125
	v_cvt_pk_bf16_f32 v122, v126, v127
	v_cvt_pk_bf16_f32 v123, v128, v129
	v_cvt_pk_bf16_f32 v124, v130, v131
	v_cvt_pk_bf16_f32 v125, v132, v133
	v_mfma_f32_32x32x16_bf16 v[68:83], v[234:237], v[118:121], v[68:83]
	v_pk_add_f32 v[16:17], v[16:17], v[226:227]
	v_pk_add_f32 v[16:17], v[16:17], v[228:229]
	v_mfma_f32_32x32x16_bf16 v[52:67], v[248:251], v[118:121], v[52:67]
	v_pk_add_f32 v[16:17], v[16:17], v[230:231]
	v_pk_add_f32 v[16:17], v[16:17], v[232:233]
	v_mfma_f32_32x32x16_bf16 v[68:83], v[244:247], v[122:125], v[68:83]
	v_pk_add_f32 v[238:239], v[238:239], v[126:127]
	v_pk_add_f32 v[238:239], v[238:239], v[128:129]
	v_mfma_f32_32x32x16_bf16 v[52:67], v[252:255], v[122:125], v[52:67]
	v_pk_add_f32 v[238:239], v[238:239], v[130:131]
	v_pk_add_f32 v[238:239], v[238:239], v[132:133]
	s_setprio 0
	v_add_f32_e32 v16, v16, v17
	v_add_f32_e32 v238, v238, v239
	v_add_f32_e32 v180, v180, v16
	v_add_f32_e32 v181, v181, v238
	s_branch .LBB0_653
.Lflt_no:
	s_cmp_gt_i32 s77, s73
	s_cbranch_scc1 .LBB0_668
	s_or_b32 s78, s77, 31
	s_cmp_lt_i32 s78, s70
	s_cbranch_scc1 .LBB0_668
	s_sub_i32 s0, s33, s78
	s_cmpk_gt_i32 s0, 0x7f
	s_cselect_b64 s[0:1], -1, 0
	s_or_b64 s[0:1], s[30:31], s[0:1]
	s_or_b64 s[80:81], s[0:1], s[36:37]
	s_and_b64 vcc, exec, s[80:81]
	s_cbranch_vccnz .LBB0_663
	v_mov_b32_e32 v185, v184
	v_mov_b32_e32 v183, v182
	v_pk_mul_f32 v[50:51], v[184:185], v[50:51]
	v_pk_mul_f32 v[48:49], v[184:185], v[48:49]
	v_pk_mul_f32 v[46:47], v[184:185], v[46:47]
	v_pk_mul_f32 v[44:45], v[184:185], v[44:45]
	v_pk_mul_f32 v[42:43], v[184:185], v[42:43]
	v_pk_mul_f32 v[40:41], v[184:185], v[40:41]
	v_pk_mul_f32 v[38:39], v[184:185], v[38:39]
	v_pk_mul_f32 v[36:37], v[184:185], v[36:37]
	v_pk_mul_f32 v[34:35], v[184:185], v[34:35]
	v_pk_mul_f32 v[32:33], v[184:185], v[32:33]
	v_pk_mul_f32 v[30:31], v[184:185], v[30:31]
	v_pk_mul_f32 v[28:29], v[184:185], v[28:29]
	v_pk_mul_f32 v[26:27], v[184:185], v[26:27]
	v_pk_mul_f32 v[24:25], v[184:185], v[24:25]
	v_pk_mul_f32 v[22:23], v[184:185], v[22:23]
	v_pk_mul_f32 v[20:21], v[186:187], v[20:21]
	v_pk_mul_f32 v[82:83], v[182:183], v[82:83]
	v_pk_mul_f32 v[80:81], v[182:183], v[80:81]
	v_pk_mul_f32 v[78:79], v[182:183], v[78:79]
	v_pk_mul_f32 v[76:77], v[182:183], v[76:77]
	v_pk_mul_f32 v[74:75], v[182:183], v[74:75]
	v_pk_mul_f32 v[72:73], v[182:183], v[72:73]
	v_pk_mul_f32 v[70:71], v[182:183], v[70:71]
	v_pk_mul_f32 v[68:69], v[188:189], v[68:69]
	v_pk_mul_f32 v[66:67], v[182:183], v[66:67]
	v_pk_mul_f32 v[64:65], v[182:183], v[64:65]
	v_pk_mul_f32 v[62:63], v[182:183], v[62:63]
	v_pk_mul_f32 v[60:61], v[182:183], v[60:61]
	v_pk_mul_f32 v[58:59], v[182:183], v[58:59]
	v_pk_mul_f32 v[56:57], v[182:183], v[56:57]
	v_pk_mul_f32 v[54:55], v[182:183], v[54:55]
	v_pk_mul_f32 v[52:53], v[188:189], v[52:53]
	v_pk_mul_f32 v[180:181], v[178:179], v[180:181]
	s_mov_b64 s[36:37], -1

	.amdhsa_kernel _Z10fwd_kernel6Params
		.amdhsa_group_segment_fixed_size 0
		.amdhsa_private_segment_fixed_size 0
		.amdhsa_kernarg_size 456
		.amdhsa_user_sgpr_count 2
		.amdhsa_user_sgpr_dispatch_ptr 0
		.amdhsa_user_sgpr_queue_ptr 0
		.amdhsa_user_sgpr_kernarg_segment_ptr 1
		.amdhsa_user_sgpr_dispatch_id 0
		.amdhsa_user_sgpr_kernarg_preload_length 0
		.amdhsa_user_sgpr_kernarg_preload_offset 0
		.amdhsa_user_sgpr_private_segment_size 0
		.amdhsa_uses_dynamic_stack 0
		.amdhsa_enable_private_segment 0
		.amdhsa_system_sgpr_workgroup_id_x 1
		.amdhsa_system_sgpr_workgroup_id_y 0
		.amdhsa_system_sgpr_workgroup_id_z 0
		.amdhsa_system_sgpr_workgroup_info 0
		.amdhsa_system_vgpr_workitem_id 0
		.amdhsa_next_free_vgpr 256
		.amdhsa_next_free_sgpr 100
		.amdhsa_accum_offset 256
		.amdhsa_reserve_vcc 1
		.amdhsa_float_round_mode_32 0
		.amdhsa_float_round_mode_16_64 0
		.amdhsa_float_denorm_mode_32 3
		.amdhsa_float_denorm_mode_16_64 3
		.amdhsa_dx10_clamp 1
		.amdhsa_ieee_mode 1
		.amdhsa_fp16_overflow 0
		.amdhsa_tg_split 0
		.amdhsa_exception_fp_ieee_invalid_op 0
		.amdhsa_exception_fp_denorm_src 0
		.amdhsa_exception_fp_ieee_div_zero 0
		.amdhsa_exception_fp_ieee_overflow 0
		.amdhsa_exception_fp_ieee_underflow 0
		.amdhsa_exception_fp_ieee_inexact 0
		.amdhsa_exception_int_div_zero 0
	.end_amdhsa_kernel

amdhsa.kernels:
  - .agpr_count:     0
    .args:
      - .offset:         0
        .size:           200
        .value_kind:     by_value
      - .offset:         200
        .size:           4
        .value_kind:     hidden_block_count_x
      - .offset:         204
        .size:           4
        .value_kind:     hidden_block_count_y
      - .offset:         208
        .size:           4
        .value_kind:     hidden_block_count_z
      - .offset:         212
        .size:           2
        .value_kind:     hidden_group_size_x
      - .offset:         214
        .size:           2
        .value_kind:     hidden_group_size_y
      - .offset:         216
        .size:           2
        .value_kind:     hidden_group_size_z
      - .offset:         218
        .size:           2
        .value_kind:     hidden_remainder_x
      - .offset:         220
        .size:           2
        .value_kind:     hidden_remainder_y
      - .offset:         222
        .size:           2
        .value_kind:     hidden_remainder_z
      - .offset:         240
        .size:           8
        .value_kind:     hidden_global_offset_x
      - .offset:         248
        .size:           8
        .value_kind:     hidden_global_offset_y
      - .offset:         256
        .size:           8
        .value_kind:     hidden_global_offset_z
      - .offset:         264
        .size:           2
        .value_kind:     hidden_grid_dims
      - .offset:         320
        .size:           4
        .value_kind:     hidden_dynamic_lds_size
    .group_segment_fixed_size: 0
    .kernarg_segment_align: 8
    .kernarg_segment_size: 456
    .language:       OpenCL C
    .language_version:
      - 2
      - 0
    .max_flat_workgroup_size: 512
    .name:           _Z10fwd_kernel6Params
    .private_segment_fixed_size: 0
    .sgpr_count:     106
    .sgpr_spill_count: 258
    .symbol:         _Z10fwd_kernel6Params.kd
    .uniform_work_group_size: 1
    .uses_dynamic_stack: false
    .vgpr_count:     256
    .vgpr_spill_count: 0
    .wavefront_size: 64
